# PV epilogue: results staged through LDS so each kv-group needs one 16B za load and one 16B store per lane instead of 64 two-byte memory ops
# speedup vs baseline: 1.0925x; 1.0019x over previous
.LBB0_767:
	s_or_b64 exec, exec, s[20:21]
	v_lshl_add_u32 v72, v192, 1, v8
	s_waitcnt lgkmcnt(0)
	s_barrier
	ds_read_u16 v0, v72
	ds_read_u16 v2, v72 offset:8
	ds_read_u16 v8, v72 offset:16
	ds_read_u16 v10, v72 offset:24
	ds_read_u16 v16, v72 offset:32
	ds_read_u16 v18, v72 offset:40
	ds_read_u16 v24, v72 offset:48
	ds_read_u16 v26, v72 offset:56
	s_waitcnt lgkmcnt(7)
	v_lshlrev_b32_e32 v136, 9, v0
	v_lshl_add_u64 v[0:1], v[162:163], 0, v[136:137]
	s_waitcnt lgkmcnt(6)
	v_lshlrev_b32_e32 v136, 9, v2
	v_lshl_add_u64 v[4:5], v[162:163], 0, v[136:137]
	s_waitcnt lgkmcnt(5)
	v_lshlrev_b32_e32 v136, 9, v8
	v_lshl_add_u64 v[8:9], v[162:163], 0, v[136:137]
	s_waitcnt lgkmcnt(4)
	v_lshlrev_b32_e32 v136, 9, v10
	v_lshl_add_u64 v[12:13], v[162:163], 0, v[136:137]
	s_waitcnt lgkmcnt(3)
	v_lshlrev_b32_e32 v136, 9, v16
	v_lshl_add_u64 v[16:17], v[162:163], 0, v[136:137]
	s_waitcnt lgkmcnt(2)
	v_lshlrev_b32_e32 v136, 9, v18
	v_lshl_add_u64 v[20:21], v[162:163], 0, v[136:137]
	s_waitcnt lgkmcnt(1)
	v_lshlrev_b32_e32 v136, 9, v24
	v_lshl_add_u64 v[24:25], v[162:163], 0, v[136:137]
	s_waitcnt lgkmcnt(0)
	v_lshlrev_b32_e32 v136, 9, v26
	global_load_dwordx4 v[0:3], v[0:1], off
	s_nop 0
	global_load_dwordx4 v[4:7], v[4:5], off
	s_nop 0
	global_load_dwordx4 v[8:11], v[8:9], off
	s_nop 0
	global_load_dwordx4 v[12:15], v[12:13], off
	s_nop 0
	global_load_dwordx4 v[16:19], v[16:17], off
	s_nop 0
	global_load_dwordx4 v[20:23], v[20:21], off
	v_lshl_add_u64 v[30:31], v[162:163], 0, v[136:137]
	global_load_dwordx4 v[24:27], v[24:25], off
	s_nop 0
	global_load_dwordx4 v[36:39], v[30:31], off
	v_cmp_eq_u32_e64 s[0:1], 3, v29
	s_or_b64 s[0:1], vcc, s[0:1]
	v_cmp_lt_u32_e32 vcc, 1, v29
	v_cndmask_b32_e64 v30, v237, 0, s[0:1]
	v_ashrrev_i32_e32 v29, 31, v28
	v_cndmask_b32_e32 v31, 0, v238, vcc
	v_lshlrev_b64 v[52:53], 10, v[28:29]
	v_lshlrev_b64 v[28:29], 11, v[28:29]
	v_add3_u32 v56, 0, v30, v31
	v_mov_b32_e32 v253, v56
	v_lshl_add_u64 v[54:55], v[160:161], 0, v[28:29]
	v_add_u32_e32 v28, v56, v196
	v_add_u32_e32 v29, v56, v197
	v_add_u32_e32 v32, v56, v198
	v_add_u32_e32 v33, v56, v199
	v_add_u32_e32 v34, v56, v202
	v_add_u32_e32 v35, v56, v203
	v_add_u32_e32 v40, v56, v204
	v_add_u32_e32 v41, v56, v205
	v_or_b32_e32 v30, v31, v30
	s_mov_b32 s24, 0
	v_add_u32_e32 v58, v232, v30
	s_mov_b64 s[20:21], -1
	v_add_u32_e32 v73, v28, v193
	v_add_u32_e32 v74, v29, v193
	v_add_u32_e32 v75, v32, v193
	v_add_u32_e32 v76, v33, v193
	v_add_u32_e32 v59, v34, v200
	v_add_u32_e32 v60, v35, v200
	v_add_u32_e32 v61, v40, v200
	v_add_u32_e32 v62, v41, v200
	s_branch .LBB0_769

.LBB0_791:
	v_lshlrev_b32_e32 v136, 4, v235
	v_lshl_or_b32 v136, s2, 10, v136
	v_lshl_add_u64 v[94:95], v[68:69], 0, v[136:137]
	global_load_dwordx4 v[96:99], v[94:95], off nt
	v_lshl_add_u64 v[120:121], v[66:67], 0, v[136:137]
	v_lshl_add_u32 v70, v235, 2, v253
	v_lshl_add_u32 v71, v235, 5, v253
	s_and_saveexec_b64 s[20:21], s[14:15]
	ds_write_b32 v70, v60 offset:8192
	ds_write_b32 v70, v61 offset:8704
	ds_write_b32 v70, v62 offset:9216
	ds_write_b32 v70, v63 offset:9728
	ds_write_b32 v70, v56 offset:8256
	ds_write_b32 v70, v57 offset:8768
	ds_write_b32 v70, v58 offset:9280
	ds_write_b32 v70, v59 offset:9792
	ds_write_b32 v70, v52 offset:8320
	ds_write_b32 v70, v53 offset:8832
	ds_write_b32 v70, v54 offset:9344
	ds_write_b32 v70, v55 offset:9856
	ds_write_b32 v70, v48 offset:8384
	ds_write_b32 v70, v49 offset:8896
	ds_write_b32 v70, v50 offset:9408
	ds_write_b32 v70, v51 offset:9920
	ds_write_b32 v70, v44 offset:8448
	ds_write_b32 v70, v45 offset:8960
	ds_write_b32 v70, v46 offset:9472
	ds_write_b32 v70, v47 offset:9984
	ds_write_b32 v70, v40 offset:8512
	ds_write_b32 v70, v41 offset:9024
	ds_write_b32 v70, v42 offset:9536
	ds_write_b32 v70, v43 offset:10048
	ds_write_b32 v70, v36 offset:8576
	ds_write_b32 v70, v37 offset:9088
	ds_write_b32 v70, v38 offset:9600
	ds_write_b32 v70, v39 offset:10112
	ds_write_b32 v70, v32 offset:8640
	ds_write_b32 v70, v33 offset:9152
	ds_write_b32 v70, v34 offset:9664
	ds_write_b32 v70, v35 offset:10176
	s_or_b64 exec, exec, s[20:21]
	s_waitcnt lgkmcnt(0)
	ds_read_b128 v[100:103], v71 offset:8192
	ds_read_b128 v[104:107], v71 offset:8208
	s_waitcnt vmcnt(0) lgkmcnt(0)
	v_lshlrev_b32_e32 v108, 16, v96
	v_and_b32_e32 v109, 0xffff0000, v96
	v_mul_f32_e32 v108, v100, v108
	v_mul_f32_e32 v109, v101, v109
	v_bfe_u32 v110, v108, 16, 1
	v_bfe_u32 v111, v109, 16, 1
	v_add3_u32 v108, v108, v110, s79
	v_add3_u32 v109, v109, v111, s79
	v_lshrrev_b32_e32 v108, 16, v108
	v_and_or_b32 v116, v109, s80, v108
	v_lshlrev_b32_e32 v108, 16, v97
	v_and_b32_e32 v109, 0xffff0000, v97
	v_mul_f32_e32 v108, v102, v108
	v_mul_f32_e32 v109, v103, v109
	v_bfe_u32 v110, v108, 16, 1
	v_bfe_u32 v111, v109, 16, 1
	v_add3_u32 v108, v108, v110, s79
	v_add3_u32 v109, v109, v111, s79
	v_lshrrev_b32_e32 v108, 16, v108
	v_and_or_b32 v117, v109, s80, v108
	v_lshlrev_b32_e32 v108, 16, v98
	v_and_b32_e32 v109, 0xffff0000, v98
	v_mul_f32_e32 v108, v104, v108
	v_mul_f32_e32 v109, v105, v109
	v_bfe_u32 v110, v108, 16, 1
	v_bfe_u32 v111, v109, 16, 1
	v_add3_u32 v108, v108, v110, s79
	v_add3_u32 v109, v109, v111, s79
	v_lshrrev_b32_e32 v108, 16, v108
	v_and_or_b32 v118, v109, s80, v108
	v_lshlrev_b32_e32 v108, 16, v99
	v_and_b32_e32 v109, 0xffff0000, v99
	v_mul_f32_e32 v108, v106, v108
	v_mul_f32_e32 v109, v107, v109
	v_bfe_u32 v110, v108, 16, 1
	v_bfe_u32 v111, v109, 16, 1
	v_add3_u32 v108, v108, v110, s79
	v_add3_u32 v109, v109, v111, s79
	v_lshrrev_b32_e32 v108, 16, v108
	v_and_or_b32 v119, v109, s80, v108
	global_store_dwordx4 v[120:121], v[116:119], off nt
	s_branch .LBB0_786
